# combined: hand-scheduled RWKV scan loop + batched adaLN-modulation GEMV loads + packed-f32 SwiGLU epilogues
# baseline (speedup 1.0000x reference)
.LBB0_695:
	s_lshl_b32 s2, s20, 1
	s_and_b32 s2, s2, 14
	s_ashr_i32 s3, s20, 7
	s_add_i32 s2, s2, s3
	s_and_b32 s5, s2, 7
	s_lshl_b32 s2, s2, 11
	s_lshr_b32 s3, s20, 1
	s_and_b32 s2, s2, 0xffffc000
	s_and_b32 s4, s3, 60
	s_ashr_i32 s3, s2, 31
	s_lshl_b64 s[22:23], s[2:3], 13
	s_lshl_b32 s21, s5, 10
	s_add_u32 s22, s12, s22
	s_addc_u32 s23, s13, s23
	v_mbcnt_lo_u32_b32 v8, -1, 0
	v_mbcnt_hi_u32_b32 v8, -1, v8
	s_add_u32 s22, s22, s21
	v_lshlrev_b32_e32 v0, 4, v8
	s_addc_u32 s23, s23, 0
	v_ashrrev_i32_e32 v1, 31, v0
	v_lshl_add_u64 v[4:5], s[22:23], 0, v[0:1]
	s_mov_b32 m0, s43
	s_add_i32 s22, 0, 0x20800
	global_load_lds_dwordx4 v[4:5], off
	v_lshl_add_u64 v[4:5], v[4:5], 0, s[14:15]
	s_mov_b32 m0, s46
	v_and_b32_e32 v1, 31, v8
	global_load_lds_dwordx4 v[4:5], off
	v_lshl_add_u64 v[4:5], v[4:5], 0, s[14:15]
	s_mov_b32 m0, s47
	v_or_b32_e32 v2, s2, v1
	global_load_lds_dwordx4 v[4:5], off
	v_lshl_add_u64 v[4:5], v[4:5], 0, s[14:15]
	s_mov_b32 m0, s22
	v_mov_b32_e32 v3, s3
	global_load_lds_dwordx4 v[4:5], off
	v_lshl_add_u64 v[4:5], v[4:5], 0, s[14:15]
	s_mov_b32 m0, s48
	v_lshlrev_b64 v[2:3], 12, v[2:3]
	global_load_lds_dwordx4 v[4:5], off
	v_lshl_add_u64 v[4:5], v[4:5], 0, s[14:15]
	s_mov_b32 m0, s49
	v_lshl_add_u64 v[2:3], s[6:7], 0, v[2:3]
	global_load_lds_dwordx4 v[4:5], off
	v_lshl_add_u64 v[4:5], v[4:5], 0, s[14:15]
	s_mov_b32 m0, s50
	s_lshl_b32 s24, s5, 7
	global_load_lds_dwordx4 v[4:5], off
	v_lshl_add_u64 v[4:5], v[4:5], 0, s[14:15]
	s_mov_b32 m0, s51
	s_add_i32 s23, 0, 0x23c00
	global_load_lds_dwordx4 v[4:5], off
	v_lshl_add_u64 v[4:5], v[4:5], 0, s[14:15]
	s_mov_b32 m0, s52
	v_lshl_add_u64 v[2:3], v[2:3], 0, s[24:25]
	global_load_lds_dwordx4 v[4:5], off
	v_lshl_add_u64 v[4:5], v[4:5], 0, s[14:15]
	s_mov_b32 m0, s53
	s_lshl_b32 s24, s4, 1
	global_load_lds_dwordx4 v[4:5], off
	v_lshl_add_u64 v[4:5], v[4:5], 0, s[14:15]
	s_mov_b32 m0, s54
	v_lshl_add_u64 v[2:3], v[2:3], 0, s[24:25]
	global_load_lds_dwordx4 v[4:5], off
	v_lshl_add_u64 v[4:5], v[4:5], 0, s[14:15]
	s_mov_b32 m0, s55
	s_add_i32 s24, 0, 0x24000
	global_load_lds_dwordx4 v[4:5], off
	v_lshl_add_u64 v[4:5], v[4:5], 0, s[14:15]
	s_mov_b32 m0, s56
	s_add_i32 s26, 0, 0x27000
	global_load_lds_dwordx4 v[4:5], off
	v_lshl_add_u64 v[4:5], v[4:5], 0, s[14:15]
	s_mov_b32 m0, s57
	v_ashrrev_i32_e32 v9, 5, v8
	global_load_lds_dwordx4 v[4:5], off
	v_lshl_add_u64 v[4:5], v[4:5], 0, s[14:15]
	s_mov_b32 m0, s58
	v_lshlrev_b32_e32 v6, 1, v9
	global_load_lds_dwordx4 v[4:5], off
	v_lshl_add_u64 v[4:5], v[4:5], 0, s[14:15]
	s_mov_b32 m0, s59
	v_ashrrev_i32_e32 v7, 31, v6
	global_load_lds_dwordx4 v[4:5], off
	v_lshl_add_u64 v[4:5], v[4:5], 0, s[14:15]
	s_mov_b32 m0, s23
	s_lshl_b32 s21, s5, 6
	global_load_lds_dwordx4 v[4:5], off
	v_lshl_add_u64 v[4:5], v[4:5], 0, s[14:15]
	s_mov_b32 m0, s24
	v_lshl_add_u64 v[2:3], v[6:7], 1, v[2:3]
	global_load_lds_dwordx4 v[4:5], off
	v_lshl_add_u64 v[4:5], v[4:5], 0, s[14:15]
	s_mov_b32 m0, s60
	v_and_b32_e32 v0, 0xf0, v0
	global_load_lds_dwordx4 v[4:5], off
	v_lshl_add_u64 v[4:5], v[4:5], 0, s[14:15]
	s_mov_b32 m0, s61
	v_add_u32_e32 v27, s43, v0
	global_load_lds_dwordx4 v[4:5], off
	v_lshl_add_u64 v[4:5], v[4:5], 0, s[14:15]
	s_mov_b32 m0, s62
	v_add_u32_e32 v36, s74, v0
	global_load_lds_dwordx4 v[4:5], off
	v_lshl_add_u64 v[4:5], v[4:5], 0, s[14:15]
	s_mov_b32 m0, s63
	s_nop 0
	global_load_lds_dwordx4 v[4:5], off
	v_lshl_add_u64 v[4:5], v[4:5], 0, s[14:15]
	s_mov_b32 m0, s64
	s_nop 0
	global_load_lds_dwordx4 v[4:5], off
	v_lshl_add_u64 v[4:5], v[4:5], 0, s[14:15]
	s_mov_b32 m0, s65
	s_nop 0
	global_load_lds_dwordx4 v[4:5], off
	v_lshl_add_u64 v[4:5], v[4:5], 0, s[14:15]
	s_mov_b32 m0, s66
	s_nop 0
	global_load_lds_dwordx4 v[4:5], off
	v_lshl_add_u64 v[4:5], v[4:5], 0, s[14:15]
	s_mov_b32 m0, s67
	s_nop 0
	global_load_lds_dwordx4 v[4:5], off
	v_lshl_add_u64 v[4:5], v[4:5], 0, s[14:15]
	s_mov_b32 m0, s69
	s_nop 0
	global_load_lds_dwordx4 v[4:5], off
	v_lshl_add_u64 v[4:5], v[4:5], 0, s[14:15]
	s_mov_b32 m0, s70
	s_nop 0
	global_load_lds_dwordx4 v[4:5], off
	v_lshl_add_u64 v[4:5], v[4:5], 0, s[14:15]
	s_mov_b32 m0, s71
	s_nop 0
	global_load_lds_dwordx4 v[4:5], off
	v_lshl_add_u64 v[4:5], v[4:5], 0, s[14:15]
	s_mov_b32 m0, s26
	s_nop 0
	global_load_lds_dwordx4 v[4:5], off
	v_lshl_add_u64 v[4:5], v[4:5], 0, s[14:15]
	s_mov_b32 m0, s72
	s_nop 0
	global_load_lds_dwordx4 v[4:5], off
	v_lshl_add_u64 v[4:5], v[4:5], 0, s[14:15]
	s_mov_b32 m0, s73
	s_nop 0
	global_load_lds_dwordx4 v[4:5], off
	v_lshl_add_u64 v[30:31], v[4:5], 0, s[14:15]
	v_ashrrev_i32_e32 v4, 4, v8
	s_waitcnt vmcnt(0)
	v_add_u32_e32 v26, s4, v4
	s_mov_b64 s[4:5], 0x155ffc00
	v_lshl_add_u64 v[28:29], v[2:3], 0, s[4:5]
	v_lshl_add_u32 v37, v26, 2, s75
	s_setprio 3
	v_lshlrev_b32_e32 v0, 2, v4
	v_lshl_add_u32 v2, v1, 4, 0
	v_lshlrev_b32_e32 v3, 3, v9
	v_mov_b32_e32 v42, 0
	v_sub_u32_e32 v38, 0, v1
	s_mov_b32 s27, 0
	v_add_u32_e32 v39, 0, v0
	v_add_u32_e32 v40, v2, v3
	v_mov_b32_e32 v41, 0
	v_mov_b32_e32 v32, 0
	v_mov_b32_e32 v33, v42
	v_mov_b32_e32 v34, 0
	v_mov_b32_e32 v35, v42
	v_mov_b32_e32 v18, 0
	v_mov_b32_e32 v19, v42
	v_mov_b32_e32 v20, v42
	v_mov_b32_e32 v21, v42
	v_mov_b32_e32 v0, 0
	v_mov_b32_e32 v1, v42
	v_mov_b32_e32 v2, v42
	v_mov_b32_e32 v3, v42
	v_mov_b32_e32 v12, 0
	v_mov_b32_e32 v13, v42
	v_mov_b32_e32 v14, v42
	v_mov_b32_e32 v15, v42
	v_mov_b32_e32 v4, 0
	v_mov_b32_e32 v5, v42
	v_mov_b32_e32 v6, v42
	v_mov_b32_e32 v7, v42
	v_mov_b32_e32 v22, 0
	v_mov_b32_e32 v23, v42
	v_mov_b32_e32 v24, v42
	v_mov_b32_e32 v25, v42
	v_mov_b32_e32 v8, 0
	v_mov_b32_e32 v9, v42
	v_mov_b32_e32 v10, v42
	v_mov_b32_e32 v11, v42
	v_readfirstlane_b32 s100, v30
	v_readfirstlane_b32 s101, v31
	v_mov_b32_e32 v68, 0
	v_mov_b32_e32 v69, 0
	ds_write_b64 v40, v[68:69] offset:60416
	ds_read_b128 v[0:3], v27 offset:0
	ds_read_b128 v[4:7], v36 offset:0
	ds_read_b128 v[8:11], v36 offset:256
	ds_read_b32 v41, v37 offset:0
	ds_read_b128 v[12:15], v27 offset:1024
	ds_read_b128 v[18:21], v36 offset:1024
	ds_read_b128 v[22:25], v36 offset:1280
	ds_read_b32 v31, v37 offset:1024
	v_subrev_u32_e32 v30, s100, v30
	v_mov_b32_e32 v58, 0
	v_mov_b32_e32 v59, 0
	s_mov_b32 m0, s43
	s_waitcnt lgkmcnt(0)
.Lscan_loop:
	v_cvt_pkrtz_f16_f32 v54, v32, v33
	v_dot2_f32_f16 v56, v6, v54, 0
	v_dot2_f32_f16 v57, v58, v54, 0
	v_cvt_pkrtz_f16_f32 v55, v34, v35
	v_pk_mul_f32 v[32:33], v[32:33], v[0:1]
	v_dot2c_f32_f16_e32 v56, v7, v55
	v_dot2c_f32_f16_e32 v57, v59, v55
	v_pk_mul_f32 v[34:35], v[34:35], v[2:3]
	ds_read_b128 v[42:45], v27 offset:2048
	v_add_f32_dpp v56, v56, v56 quad_perm:[1,0,3,2] row_mask:0xf bank_mask:0xf bound_ctrl:1
	ds_read_b128 v[46:49], v36 offset:2048
	ds_read_b128 v[50:53], v36 offset:2304
	v_add_f32_dpp v56, v56, v56 quad_perm:[2,3,0,1] row_mask:0xf bank_mask:0xf bound_ctrl:1
	ds_read_b32 v66, v37 offset:2048
	global_load_lds_dwordx4 v30, s[100:101]
	v_add_f32_dpp v56, v56, v56 row_half_mirror row_mask:0xf bank_mask:0xf bound_ctrl:1
	v_add_f32_dpp v57, v57, v57 quad_perm:[1,0,3,2] row_mask:0xf bank_mask:0xf bound_ctrl:1
	v_add_u32_e32 v30, s14, v30
	v_add_f32_dpp v56, v56, v56 row_mirror row_mask:0xf bank_mask:0xf bound_ctrl:1
	v_cvt_pkrtz_f16_f32 v56, v41, v56
	v_add_f32_dpp v57, v57, v57 quad_perm:[2,3,0,1] row_mask:0xf bank_mask:0xf bound_ctrl:1
	v_dot2c_f32_f16_e32 v32, v8, v56
	v_dot2c_f32_f16_e32 v33, v9, v56
	v_add_f32_dpp v57, v57, v57 row_half_mirror row_mask:0xf bank_mask:0xf bound_ctrl:1
	v_dot2c_f32_f16_e32 v34, v10, v56
	v_dot2c_f32_f16_e32 v35, v11, v56
	v_add_f32_dpp v57, v57, v57 row_mirror row_mask:0xf bank_mask:0xf bound_ctrl:1
	s_mov_b32 m0, s46
	ds_write_b32 v39, v57 offset:60416
	s_waitcnt vmcnt(29) lgkmcnt(7)
	v_cvt_pkrtz_f16_f32 v0, v32, v33
	v_dot2_f32_f16 v2, v20, v0, 0
	v_dot2_f32_f16 v3, v4, v0, 0
	v_cvt_pkrtz_f16_f32 v1, v34, v35
	v_pk_mul_f32 v[32:33], v[32:33], v[12:13]
	v_dot2c_f32_f16_e32 v2, v21, v1
	v_dot2c_f32_f16_e32 v3, v5, v1
	v_pk_mul_f32 v[34:35], v[34:35], v[14:15]
	ds_read_b128 v[54:57], v27 offset:3072
	v_add_f32_dpp v2, v2, v2 quad_perm:[1,0,3,2] row_mask:0xf bank_mask:0xf bound_ctrl:1
	ds_read_b128 v[58:61], v36 offset:3072
	ds_read_b128 v[62:65], v36 offset:3328
	v_add_f32_dpp v2, v2, v2 quad_perm:[2,3,0,1] row_mask:0xf bank_mask:0xf bound_ctrl:1
	ds_read_b32 v67, v37 offset:3072
	global_load_lds_dwordx4 v30, s[100:101]
	v_add_f32_dpp v2, v2, v2 row_half_mirror row_mask:0xf bank_mask:0xf bound_ctrl:1
	v_add_f32_dpp v3, v3, v3 quad_perm:[1,0,3,2] row_mask:0xf bank_mask:0xf bound_ctrl:1
	v_add_u32_e32 v30, s14, v30
	v_add_f32_dpp v2, v2, v2 row_mirror row_mask:0xf bank_mask:0xf bound_ctrl:1
	v_cvt_pkrtz_f16_f32 v2, v31, v2
	v_add_f32_dpp v3, v3, v3 quad_perm:[2,3,0,1] row_mask:0xf bank_mask:0xf bound_ctrl:1
	v_dot2c_f32_f16_e32 v32, v22, v2
	v_dot2c_f32_f16_e32 v33, v23, v2
	v_add_f32_dpp v3, v3, v3 row_half_mirror row_mask:0xf bank_mask:0xf bound_ctrl:1
	v_dot2c_f32_f16_e32 v34, v24, v2
	v_dot2c_f32_f16_e32 v35, v25, v2
	v_add_f32_dpp v3, v3, v3 row_mirror row_mask:0xf bank_mask:0xf bound_ctrl:1
	s_mov_b32 m0, s47
	ds_write_b32 v39, v3 offset:60432
	s_waitcnt vmcnt(29) lgkmcnt(6)
	v_cvt_pkrtz_f16_f32 v12, v32, v33
	v_dot2_f32_f16 v14, v48, v12, 0
	v_dot2_f32_f16 v15, v18, v12, 0
	v_cvt_pkrtz_f16_f32 v13, v34, v35
	v_pk_mul_f32 v[32:33], v[32:33], v[42:43]
	v_dot2c_f32_f16_e32 v14, v49, v13
	v_dot2c_f32_f16_e32 v15, v19, v13
	v_pk_mul_f32 v[34:35], v[34:35], v[44:45]
	ds_read_b128 v[0:3], v27 offset:4096
	v_add_f32_dpp v14, v14, v14 quad_perm:[1,0,3,2] row_mask:0xf bank_mask:0xf bound_ctrl:1
	ds_read_b128 v[4:7], v36 offset:4096
	ds_read_b128 v[8:11], v36 offset:4352
	v_add_f32_dpp v14, v14, v14 quad_perm:[2,3,0,1] row_mask:0xf bank_mask:0xf bound_ctrl:1
	ds_read_b32 v41, v37 offset:4096
	global_load_lds_dwordx4 v30, s[100:101]
	v_add_f32_dpp v14, v14, v14 row_half_mirror row_mask:0xf bank_mask:0xf bound_ctrl:1
	v_add_f32_dpp v15, v15, v15 quad_perm:[1,0,3,2] row_mask:0xf bank_mask:0xf bound_ctrl:1
	v_add_u32_e32 v30, s14, v30
	v_add_f32_dpp v14, v14, v14 row_mirror row_mask:0xf bank_mask:0xf bound_ctrl:1
	v_cvt_pkrtz_f16_f32 v14, v66, v14
	v_add_f32_dpp v15, v15, v15 quad_perm:[2,3,0,1] row_mask:0xf bank_mask:0xf bound_ctrl:1
	v_dot2c_f32_f16_e32 v32, v50, v14
	v_dot2c_f32_f16_e32 v33, v51, v14
	v_add_f32_dpp v15, v15, v15 row_half_mirror row_mask:0xf bank_mask:0xf bound_ctrl:1
	v_dot2c_f32_f16_e32 v34, v52, v14
	v_dot2c_f32_f16_e32 v35, v53, v14
	v_add_f32_dpp v15, v15, v15 row_mirror row_mask:0xf bank_mask:0xf bound_ctrl:1
	s_mov_b32 m0, s22
	ds_write_b32 v39, v15 offset:60448
	s_waitcnt vmcnt(29) lgkmcnt(6)
	v_cvt_pkrtz_f16_f32 v42, v32, v33
	v_dot2_f32_f16 v44, v60, v42, 0
	v_dot2_f32_f16 v45, v46, v42, 0
	v_cvt_pkrtz_f16_f32 v43, v34, v35
	v_pk_mul_f32 v[32:33], v[32:33], v[54:55]
	v_dot2c_f32_f16_e32 v44, v61, v43
	v_dot2c_f32_f16_e32 v45, v47, v43
	v_pk_mul_f32 v[34:35], v[34:35], v[56:57]
	ds_read_b128 v[12:15], v27 offset:5120
	v_add_f32_dpp v44, v44, v44 quad_perm:[1,0,3,2] row_mask:0xf bank_mask:0xf bound_ctrl:1
	ds_read_b128 v[18:21], v36 offset:5120
	ds_read_b128 v[22:25], v36 offset:5376
	v_add_f32_dpp v44, v44, v44 quad_perm:[2,3,0,1] row_mask:0xf bank_mask:0xf bound_ctrl:1
	ds_read_b32 v31, v37 offset:5120
	global_load_lds_dwordx4 v30, s[100:101]
	v_add_f32_dpp v44, v44, v44 row_half_mirror row_mask:0xf bank_mask:0xf bound_ctrl:1
	v_add_f32_dpp v45, v45, v45 quad_perm:[1,0,3,2] row_mask:0xf bank_mask:0xf bound_ctrl:1
	v_add_u32_e32 v30, s14, v30
	v_add_f32_dpp v44, v44, v44 row_mirror row_mask:0xf bank_mask:0xf bound_ctrl:1
	v_cvt_pkrtz_f16_f32 v44, v67, v44
	v_add_f32_dpp v45, v45, v45 quad_perm:[2,3,0,1] row_mask:0xf bank_mask:0xf bound_ctrl:1
	v_dot2c_f32_f16_e32 v32, v62, v44
	v_dot2c_f32_f16_e32 v33, v63, v44
	v_add_f32_dpp v45, v45, v45 row_half_mirror row_mask:0xf bank_mask:0xf bound_ctrl:1
	v_dot2c_f32_f16_e32 v34, v64, v44
	v_dot2c_f32_f16_e32 v35, v65, v44
	v_add_f32_dpp v45, v45, v45 row_mirror row_mask:0xf bank_mask:0xf bound_ctrl:1
	s_mov_b32 m0, s48
	ds_write_b32 v39, v45 offset:60464
	s_waitcnt vmcnt(29) lgkmcnt(6)
	v_cvt_pkrtz_f16_f32 v54, v32, v33
	v_dot2_f32_f16 v56, v6, v54, 0
	v_dot2_f32_f16 v57, v58, v54, 0
	v_cvt_pkrtz_f16_f32 v55, v34, v35
	v_pk_mul_f32 v[32:33], v[32:33], v[0:1]
	v_dot2c_f32_f16_e32 v56, v7, v55
	v_dot2c_f32_f16_e32 v57, v59, v55
	v_pk_mul_f32 v[34:35], v[34:35], v[2:3]
	ds_read_b128 v[42:45], v27 offset:6144
	v_add_f32_dpp v56, v56, v56 quad_perm:[1,0,3,2] row_mask:0xf bank_mask:0xf bound_ctrl:1
	ds_read_b128 v[46:49], v36 offset:6144
	ds_read_b128 v[50:53], v36 offset:6400
	v_add_f32_dpp v56, v56, v56 quad_perm:[2,3,0,1] row_mask:0xf bank_mask:0xf bound_ctrl:1
	ds_read_b32 v66, v37 offset:6144
	global_load_lds_dwordx4 v30, s[100:101]
	v_add_f32_dpp v56, v56, v56 row_half_mirror row_mask:0xf bank_mask:0xf bound_ctrl:1
	v_add_f32_dpp v57, v57, v57 quad_perm:[1,0,3,2] row_mask:0xf bank_mask:0xf bound_ctrl:1
	v_add_u32_e32 v30, s14, v30
	v_add_f32_dpp v56, v56, v56 row_mirror row_mask:0xf bank_mask:0xf bound_ctrl:1
	v_cvt_pkrtz_f16_f32 v56, v41, v56
	v_add_f32_dpp v57, v57, v57 quad_perm:[2,3,0,1] row_mask:0xf bank_mask:0xf bound_ctrl:1
	v_dot2c_f32_f16_e32 v32, v8, v56
	v_dot2c_f32_f16_e32 v33, v9, v56
	v_add_f32_dpp v57, v57, v57 row_half_mirror row_mask:0xf bank_mask:0xf bound_ctrl:1
	v_dot2c_f32_f16_e32 v34, v10, v56
	v_dot2c_f32_f16_e32 v35, v11, v56
	v_add_f32_dpp v57, v57, v57 row_mirror row_mask:0xf bank_mask:0xf bound_ctrl:1
	s_mov_b32 m0, s49
	ds_write_b32 v39, v57 offset:60480
	s_waitcnt vmcnt(29) lgkmcnt(6)
	v_cvt_pkrtz_f16_f32 v0, v32, v33
	v_dot2_f32_f16 v2, v20, v0, 0
	v_dot2_f32_f16 v3, v4, v0, 0
	v_cvt_pkrtz_f16_f32 v1, v34, v35
	v_pk_mul_f32 v[32:33], v[32:33], v[12:13]
	v_dot2c_f32_f16_e32 v2, v21, v1
	v_dot2c_f32_f16_e32 v3, v5, v1
	v_pk_mul_f32 v[34:35], v[34:35], v[14:15]
	ds_read_b128 v[54:57], v27 offset:7168
	v_add_f32_dpp v2, v2, v2 quad_perm:[1,0,3,2] row_mask:0xf bank_mask:0xf bound_ctrl:1
	ds_read_b128 v[58:61], v36 offset:7168
	ds_read_b128 v[62:65], v36 offset:7424
	v_add_f32_dpp v2, v2, v2 quad_perm:[2,3,0,1] row_mask:0xf bank_mask:0xf bound_ctrl:1
	ds_read_b32 v67, v37 offset:7168
	global_load_lds_dwordx4 v30, s[100:101]
	v_add_f32_dpp v2, v2, v2 row_half_mirror row_mask:0xf bank_mask:0xf bound_ctrl:1
	v_add_f32_dpp v3, v3, v3 quad_perm:[1,0,3,2] row_mask:0xf bank_mask:0xf bound_ctrl:1
	v_add_u32_e32 v30, s14, v30
	v_add_f32_dpp v2, v2, v2 row_mirror row_mask:0xf bank_mask:0xf bound_ctrl:1
	v_cvt_pkrtz_f16_f32 v2, v31, v2
	v_add_f32_dpp v3, v3, v3 quad_perm:[2,3,0,1] row_mask:0xf bank_mask:0xf bound_ctrl:1
	v_dot2c_f32_f16_e32 v32, v22, v2
	v_dot2c_f32_f16_e32 v33, v23, v2
	v_add_f32_dpp v3, v3, v3 row_half_mirror row_mask:0xf bank_mask:0xf bound_ctrl:1
	v_dot2c_f32_f16_e32 v34, v24, v2
	v_dot2c_f32_f16_e32 v35, v25, v2
	v_add_f32_dpp v3, v3, v3 row_mirror row_mask:0xf bank_mask:0xf bound_ctrl:1
	s_mov_b32 m0, s50
	ds_write_b32 v39, v3 offset:60496
	s_waitcnt vmcnt(29) lgkmcnt(6)
	v_cvt_pkrtz_f16_f32 v12, v32, v33
	v_dot2_f32_f16 v14, v48, v12, 0
	v_dot2_f32_f16 v15, v18, v12, 0
	v_cvt_pkrtz_f16_f32 v13, v34, v35
	v_pk_mul_f32 v[32:33], v[32:33], v[42:43]
	v_dot2c_f32_f16_e32 v14, v49, v13
	v_dot2c_f32_f16_e32 v15, v19, v13
	v_pk_mul_f32 v[34:35], v[34:35], v[44:45]
	ds_read_b128 v[0:3], v27 offset:8192
	v_add_f32_dpp v14, v14, v14 quad_perm:[1,0,3,2] row_mask:0xf bank_mask:0xf bound_ctrl:1
	ds_read_b128 v[4:7], v36 offset:8192
	ds_read_b128 v[8:11], v36 offset:8448
	v_add_f32_dpp v14, v14, v14 quad_perm:[2,3,0,1] row_mask:0xf bank_mask:0xf bound_ctrl:1
	ds_read_b32 v41, v37 offset:8192
	global_load_lds_dwordx4 v30, s[100:101]
	v_add_f32_dpp v14, v14, v14 row_half_mirror row_mask:0xf bank_mask:0xf bound_ctrl:1
	v_add_f32_dpp v15, v15, v15 quad_perm:[1,0,3,2] row_mask:0xf bank_mask:0xf bound_ctrl:1
	v_add_u32_e32 v30, s14, v30
	v_add_f32_dpp v14, v14, v14 row_mirror row_mask:0xf bank_mask:0xf bound_ctrl:1
	v_cvt_pkrtz_f16_f32 v14, v66, v14
	v_add_f32_dpp v15, v15, v15 quad_perm:[2,3,0,1] row_mask:0xf bank_mask:0xf bound_ctrl:1
	v_dot2c_f32_f16_e32 v32, v50, v14
	v_dot2c_f32_f16_e32 v33, v51, v14
	v_add_f32_dpp v15, v15, v15 row_half_mirror row_mask:0xf bank_mask:0xf bound_ctrl:1
	v_dot2c_f32_f16_e32 v34, v52, v14
	v_dot2c_f32_f16_e32 v35, v53, v14
	v_add_f32_dpp v15, v15, v15 row_mirror row_mask:0xf bank_mask:0xf bound_ctrl:1
	s_mov_b32 m0, s51
	ds_write_b32 v39, v15 offset:60512
	s_waitcnt vmcnt(29) lgkmcnt(6)
	v_cvt_pkrtz_f16_f32 v42, v32, v33
	v_dot2_f32_f16 v44, v60, v42, 0
	v_dot2_f32_f16 v45, v46, v42, 0
	v_cvt_pkrtz_f16_f32 v43, v34, v35
	v_pk_mul_f32 v[32:33], v[32:33], v[54:55]
	v_dot2c_f32_f16_e32 v44, v61, v43
	v_dot2c_f32_f16_e32 v45, v47, v43
	v_pk_mul_f32 v[34:35], v[34:35], v[56:57]
	ds_read_b128 v[12:15], v27 offset:9216
	v_add_f32_dpp v44, v44, v44 quad_perm:[1,0,3,2] row_mask:0xf bank_mask:0xf bound_ctrl:1
	ds_read_b128 v[18:21], v36 offset:9216
	ds_read_b128 v[22:25], v36 offset:9472
	v_add_f32_dpp v44, v44, v44 quad_perm:[2,3,0,1] row_mask:0xf bank_mask:0xf bound_ctrl:1
	ds_read_b32 v31, v37 offset:9216
	global_load_lds_dwordx4 v30, s[100:101]
	v_add_f32_dpp v44, v44, v44 row_half_mirror row_mask:0xf bank_mask:0xf bound_ctrl:1
	v_add_f32_dpp v45, v45, v45 quad_perm:[1,0,3,2] row_mask:0xf bank_mask:0xf bound_ctrl:1
	v_add_u32_e32 v30, s14, v30
	v_add_f32_dpp v44, v44, v44 row_mirror row_mask:0xf bank_mask:0xf bound_ctrl:1
	v_cvt_pkrtz_f16_f32 v44, v67, v44
	v_add_f32_dpp v45, v45, v45 quad_perm:[2,3,0,1] row_mask:0xf bank_mask:0xf bound_ctrl:1
	v_dot2c_f32_f16_e32 v32, v62, v44
	v_dot2c_f32_f16_e32 v33, v63, v44
	v_add_f32_dpp v45, v45, v45 row_half_mirror row_mask:0xf bank_mask:0xf bound_ctrl:1
	v_dot2c_f32_f16_e32 v34, v64, v44
	v_dot2c_f32_f16_e32 v35, v65, v44
	v_add_f32_dpp v45, v45, v45 row_mirror row_mask:0xf bank_mask:0xf bound_ctrl:1
	s_mov_b32 m0, s52
	ds_write_b32 v39, v45 offset:60528
	s_waitcnt vmcnt(29) lgkmcnt(6)
	v_cvt_pkrtz_f16_f32 v54, v32, v33
	v_dot2_f32_f16 v56, v6, v54, 0
	v_dot2_f32_f16 v57, v58, v54, 0
	v_cvt_pkrtz_f16_f32 v55, v34, v35
	v_pk_mul_f32 v[32:33], v[32:33], v[0:1]
	v_dot2c_f32_f16_e32 v56, v7, v55
	v_dot2c_f32_f16_e32 v57, v59, v55
	v_pk_mul_f32 v[34:35], v[34:35], v[2:3]
	ds_read_b128 v[42:45], v27 offset:10240
	v_add_f32_dpp v56, v56, v56 quad_perm:[1,0,3,2] row_mask:0xf bank_mask:0xf bound_ctrl:1
	ds_read_b128 v[46:49], v36 offset:10240
	ds_read_b128 v[50:53], v36 offset:10496
	v_add_f32_dpp v56, v56, v56 quad_perm:[2,3,0,1] row_mask:0xf bank_mask:0xf bound_ctrl:1
	ds_read_b32 v66, v37 offset:10240
	global_load_lds_dwordx4 v30, s[100:101]
	v_add_f32_dpp v56, v56, v56 row_half_mirror row_mask:0xf bank_mask:0xf bound_ctrl:1
	v_add_f32_dpp v57, v57, v57 quad_perm:[1,0,3,2] row_mask:0xf bank_mask:0xf bound_ctrl:1
	v_add_u32_e32 v30, s14, v30
	v_add_f32_dpp v56, v56, v56 row_mirror row_mask:0xf bank_mask:0xf bound_ctrl:1
	v_cvt_pkrtz_f16_f32 v56, v41, v56
	v_add_f32_dpp v57, v57, v57 quad_perm:[2,3,0,1] row_mask:0xf bank_mask:0xf bound_ctrl:1
	v_dot2c_f32_f16_e32 v32, v8, v56
	v_dot2c_f32_f16_e32 v33, v9, v56
	v_add_f32_dpp v57, v57, v57 row_half_mirror row_mask:0xf bank_mask:0xf bound_ctrl:1
	v_dot2c_f32_f16_e32 v34, v10, v56
	v_dot2c_f32_f16_e32 v35, v11, v56
	v_add_f32_dpp v57, v57, v57 row_mirror row_mask:0xf bank_mask:0xf bound_ctrl:1
	s_mov_b32 m0, s53
	ds_write_b32 v39, v57 offset:60544
	s_waitcnt vmcnt(29) lgkmcnt(6)
	v_cvt_pkrtz_f16_f32 v0, v32, v33
	v_dot2_f32_f16 v2, v20, v0, 0
	v_dot2_f32_f16 v3, v4, v0, 0
	v_cvt_pkrtz_f16_f32 v1, v34, v35
	v_pk_mul_f32 v[32:33], v[32:33], v[12:13]
	v_dot2c_f32_f16_e32 v2, v21, v1
	v_dot2c_f32_f16_e32 v3, v5, v1
	v_pk_mul_f32 v[34:35], v[34:35], v[14:15]
	ds_read_b128 v[54:57], v27 offset:11264
	v_add_f32_dpp v2, v2, v2 quad_perm:[1,0,3,2] row_mask:0xf bank_mask:0xf bound_ctrl:1
	ds_read_b128 v[58:61], v36 offset:11264
	ds_read_b128 v[62:65], v36 offset:11520
	v_add_f32_dpp v2, v2, v2 quad_perm:[2,3,0,1] row_mask:0xf bank_mask:0xf bound_ctrl:1
	ds_read_b32 v67, v37 offset:11264
	global_load_lds_dwordx4 v30, s[100:101]
	v_add_f32_dpp v2, v2, v2 row_half_mirror row_mask:0xf bank_mask:0xf bound_ctrl:1
	v_add_f32_dpp v3, v3, v3 quad_perm:[1,0,3,2] row_mask:0xf bank_mask:0xf bound_ctrl:1
	v_add_u32_e32 v30, s14, v30
	v_add_f32_dpp v2, v2, v2 row_mirror row_mask:0xf bank_mask:0xf bound_ctrl:1
	v_cvt_pkrtz_f16_f32 v2, v31, v2
	v_add_f32_dpp v3, v3, v3 quad_perm:[2,3,0,1] row_mask:0xf bank_mask:0xf bound_ctrl:1
	v_dot2c_f32_f16_e32 v32, v22, v2
	v_dot2c_f32_f16_e32 v33, v23, v2
	v_add_f32_dpp v3, v3, v3 row_half_mirror row_mask:0xf bank_mask:0xf bound_ctrl:1
	v_dot2c_f32_f16_e32 v34, v24, v2
	v_dot2c_f32_f16_e32 v35, v25, v2
	v_add_f32_dpp v3, v3, v3 row_mirror row_mask:0xf bank_mask:0xf bound_ctrl:1
	s_mov_b32 m0, s54
	ds_write_b32 v39, v3 offset:60560
	s_waitcnt vmcnt(29) lgkmcnt(6)
	v_cvt_pkrtz_f16_f32 v12, v32, v33
	v_dot2_f32_f16 v14, v48, v12, 0
	v_dot2_f32_f16 v15, v18, v12, 0
	v_cvt_pkrtz_f16_f32 v13, v34, v35
	v_pk_mul_f32 v[32:33], v[32:33], v[42:43]
	v_dot2c_f32_f16_e32 v14, v49, v13
	v_dot2c_f32_f16_e32 v15, v19, v13
	v_pk_mul_f32 v[34:35], v[34:35], v[44:45]
	ds_read_b128 v[0:3], v27 offset:12288
	v_add_f32_dpp v14, v14, v14 quad_perm:[1,0,3,2] row_mask:0xf bank_mask:0xf bound_ctrl:1
	ds_read_b128 v[4:7], v36 offset:12288
	ds_read_b128 v[8:11], v36 offset:12544
	v_add_f32_dpp v14, v14, v14 quad_perm:[2,3,0,1] row_mask:0xf bank_mask:0xf bound_ctrl:1
	ds_read_b32 v41, v37 offset:12288
	global_load_lds_dwordx4 v30, s[100:101]
	v_add_f32_dpp v14, v14, v14 row_half_mirror row_mask:0xf bank_mask:0xf bound_ctrl:1
	v_add_f32_dpp v15, v15, v15 quad_perm:[1,0,3,2] row_mask:0xf bank_mask:0xf bound_ctrl:1
	v_add_u32_e32 v30, s14, v30
	v_add_f32_dpp v14, v14, v14 row_mirror row_mask:0xf bank_mask:0xf bound_ctrl:1
	v_cvt_pkrtz_f16_f32 v14, v66, v14
	v_add_f32_dpp v15, v15, v15 quad_perm:[2,3,0,1] row_mask:0xf bank_mask:0xf bound_ctrl:1
	v_dot2c_f32_f16_e32 v32, v50, v14
	v_dot2c_f32_f16_e32 v33, v51, v14
	v_add_f32_dpp v15, v15, v15 row_half_mirror row_mask:0xf bank_mask:0xf bound_ctrl:1
	v_dot2c_f32_f16_e32 v34, v52, v14
	v_dot2c_f32_f16_e32 v35, v53, v14
	v_add_f32_dpp v15, v15, v15 row_mirror row_mask:0xf bank_mask:0xf bound_ctrl:1
	s_mov_b32 m0, s55
	ds_write_b32 v39, v15 offset:60576
	s_waitcnt vmcnt(29) lgkmcnt(6)
	v_cvt_pkrtz_f16_f32 v42, v32, v33
	v_dot2_f32_f16 v44, v60, v42, 0
	v_dot2_f32_f16 v45, v46, v42, 0
	v_cvt_pkrtz_f16_f32 v43, v34, v35
	v_pk_mul_f32 v[32:33], v[32:33], v[54:55]
	v_dot2c_f32_f16_e32 v44, v61, v43
	v_dot2c_f32_f16_e32 v45, v47, v43
	v_pk_mul_f32 v[34:35], v[34:35], v[56:57]
	ds_read_b128 v[12:15], v27 offset:13312
	v_add_f32_dpp v44, v44, v44 quad_perm:[1,0,3,2] row_mask:0xf bank_mask:0xf bound_ctrl:1
	ds_read_b128 v[18:21], v36 offset:13312
	ds_read_b128 v[22:25], v36 offset:13568
	v_add_f32_dpp v44, v44, v44 quad_perm:[2,3,0,1] row_mask:0xf bank_mask:0xf bound_ctrl:1
	ds_read_b32 v31, v37 offset:13312
	global_load_lds_dwordx4 v30, s[100:101]
	v_add_f32_dpp v44, v44, v44 row_half_mirror row_mask:0xf bank_mask:0xf bound_ctrl:1
	v_add_f32_dpp v45, v45, v45 quad_perm:[1,0,3,2] row_mask:0xf bank_mask:0xf bound_ctrl:1
	v_add_u32_e32 v30, s14, v30
	v_add_f32_dpp v44, v44, v44 row_mirror row_mask:0xf bank_mask:0xf bound_ctrl:1
	v_cvt_pkrtz_f16_f32 v44, v67, v44
	v_add_f32_dpp v45, v45, v45 quad_perm:[2,3,0,1] row_mask:0xf bank_mask:0xf bound_ctrl:1
	v_dot2c_f32_f16_e32 v32, v62, v44
	v_dot2c_f32_f16_e32 v33, v63, v44
	v_add_f32_dpp v45, v45, v45 row_half_mirror row_mask:0xf bank_mask:0xf bound_ctrl:1
	v_dot2c_f32_f16_e32 v34, v64, v44
	v_dot2c_f32_f16_e32 v35, v65, v44
	v_add_f32_dpp v45, v45, v45 row_mirror row_mask:0xf bank_mask:0xf bound_ctrl:1
	s_mov_b32 m0, s56
	ds_write_b32 v39, v45 offset:60592
	s_waitcnt vmcnt(29) lgkmcnt(6)
	v_cvt_pkrtz_f16_f32 v54, v32, v33
	v_dot2_f32_f16 v56, v6, v54, 0
	v_dot2_f32_f16 v57, v58, v54, 0
	v_cvt_pkrtz_f16_f32 v55, v34, v35
	v_pk_mul_f32 v[32:33], v[32:33], v[0:1]
	v_dot2c_f32_f16_e32 v56, v7, v55
	v_dot2c_f32_f16_e32 v57, v59, v55
	v_pk_mul_f32 v[34:35], v[34:35], v[2:3]
	ds_read_b128 v[42:45], v27 offset:14336
	v_add_f32_dpp v56, v56, v56 quad_perm:[1,0,3,2] row_mask:0xf bank_mask:0xf bound_ctrl:1
	ds_read_b128 v[46:49], v36 offset:14336
	ds_read_b128 v[50:53], v36 offset:14592
	v_add_f32_dpp v56, v56, v56 quad_perm:[2,3,0,1] row_mask:0xf bank_mask:0xf bound_ctrl:1
	ds_read_b32 v66, v37 offset:14336
	global_load_lds_dwordx4 v30, s[100:101]
	v_add_f32_dpp v56, v56, v56 row_half_mirror row_mask:0xf bank_mask:0xf bound_ctrl:1
	v_add_f32_dpp v57, v57, v57 quad_perm:[1,0,3,2] row_mask:0xf bank_mask:0xf bound_ctrl:1
	v_add_u32_e32 v30, s14, v30
	v_add_f32_dpp v56, v56, v56 row_mirror row_mask:0xf bank_mask:0xf bound_ctrl:1
	v_cvt_pkrtz_f16_f32 v56, v41, v56
	v_add_f32_dpp v57, v57, v57 quad_perm:[2,3,0,1] row_mask:0xf bank_mask:0xf bound_ctrl:1
	v_dot2c_f32_f16_e32 v32, v8, v56
	v_dot2c_f32_f16_e32 v33, v9, v56
	v_add_f32_dpp v57, v57, v57 row_half_mirror row_mask:0xf bank_mask:0xf bound_ctrl:1
	v_dot2c_f32_f16_e32 v34, v10, v56
	v_dot2c_f32_f16_e32 v35, v11, v56
	v_add_f32_dpp v57, v57, v57 row_mirror row_mask:0xf bank_mask:0xf bound_ctrl:1
	s_mov_b32 m0, s57
	ds_write_b32 v39, v57 offset:60608
	s_waitcnt vmcnt(29) lgkmcnt(6)
	v_cvt_pkrtz_f16_f32 v0, v32, v33
	v_dot2_f32_f16 v2, v20, v0, 0
	v_dot2_f32_f16 v3, v4, v0, 0
	v_cvt_pkrtz_f16_f32 v1, v34, v35
	v_pk_mul_f32 v[32:33], v[32:33], v[12:13]
	v_dot2c_f32_f16_e32 v2, v21, v1
	v_dot2c_f32_f16_e32 v3, v5, v1
	v_pk_mul_f32 v[34:35], v[34:35], v[14:15]
	ds_read_b128 v[54:57], v27 offset:15360
	v_add_f32_dpp v2, v2, v2 quad_perm:[1,0,3,2] row_mask:0xf bank_mask:0xf bound_ctrl:1
	ds_read_b128 v[58:61], v36 offset:15360
	ds_read_b128 v[62:65], v36 offset:15616
	v_add_f32_dpp v2, v2, v2 quad_perm:[2,3,0,1] row_mask:0xf bank_mask:0xf bound_ctrl:1
	ds_read_b32 v67, v37 offset:15360
	global_load_lds_dwordx4 v30, s[100:101]
	v_add_f32_dpp v2, v2, v2 row_half_mirror row_mask:0xf bank_mask:0xf bound_ctrl:1
	v_add_f32_dpp v3, v3, v3 quad_perm:[1,0,3,2] row_mask:0xf bank_mask:0xf bound_ctrl:1
	v_add_u32_e32 v30, s14, v30
	v_add_f32_dpp v2, v2, v2 row_mirror row_mask:0xf bank_mask:0xf bound_ctrl:1
	v_cvt_pkrtz_f16_f32 v2, v31, v2
	v_add_f32_dpp v3, v3, v3 quad_perm:[2,3,0,1] row_mask:0xf bank_mask:0xf bound_ctrl:1
	v_dot2c_f32_f16_e32 v32, v22, v2
	v_dot2c_f32_f16_e32 v33, v23, v2
	v_add_f32_dpp v3, v3, v3 row_half_mirror row_mask:0xf bank_mask:0xf bound_ctrl:1
	v_dot2c_f32_f16_e32 v34, v24, v2
	v_dot2c_f32_f16_e32 v35, v25, v2
	v_add_f32_dpp v3, v3, v3 row_mirror row_mask:0xf bank_mask:0xf bound_ctrl:1
	s_mov_b32 m0, s58
	ds_write_b32 v39, v3 offset:60624
	s_waitcnt vmcnt(29) lgkmcnt(6)
	v_cvt_pkrtz_f16_f32 v12, v32, v33
	v_dot2_f32_f16 v14, v48, v12, 0
	v_dot2_f32_f16 v15, v18, v12, 0
	v_cvt_pkrtz_f16_f32 v13, v34, v35
	v_pk_mul_f32 v[32:33], v[32:33], v[42:43]
	v_dot2c_f32_f16_e32 v14, v49, v13
	v_dot2c_f32_f16_e32 v15, v19, v13
	v_pk_mul_f32 v[34:35], v[34:35], v[44:45]
	ds_read_b128 v[0:3], v27 offset:16384
	v_add_f32_dpp v14, v14, v14 quad_perm:[1,0,3,2] row_mask:0xf bank_mask:0xf bound_ctrl:1
	ds_read_b128 v[4:7], v36 offset:16384
	ds_read_b128 v[8:11], v36 offset:16640
	v_add_f32_dpp v14, v14, v14 quad_perm:[2,3,0,1] row_mask:0xf bank_mask:0xf bound_ctrl:1
	ds_read_b32 v41, v37 offset:16384
	global_load_lds_dwordx4 v30, s[100:101]
	v_add_f32_dpp v14, v14, v14 row_half_mirror row_mask:0xf bank_mask:0xf bound_ctrl:1
	v_add_f32_dpp v15, v15, v15 quad_perm:[1,0,3,2] row_mask:0xf bank_mask:0xf bound_ctrl:1
	v_add_u32_e32 v30, s14, v30
	v_add_f32_dpp v14, v14, v14 row_mirror row_mask:0xf bank_mask:0xf bound_ctrl:1
	v_cvt_pkrtz_f16_f32 v14, v66, v14
	v_add_f32_dpp v15, v15, v15 quad_perm:[2,3,0,1] row_mask:0xf bank_mask:0xf bound_ctrl:1
	v_dot2c_f32_f16_e32 v32, v50, v14
	v_dot2c_f32_f16_e32 v33, v51, v14
	v_add_f32_dpp v15, v15, v15 row_half_mirror row_mask:0xf bank_mask:0xf bound_ctrl:1
	v_dot2c_f32_f16_e32 v34, v52, v14
	v_dot2c_f32_f16_e32 v35, v53, v14
	v_add_f32_dpp v15, v15, v15 row_mirror row_mask:0xf bank_mask:0xf bound_ctrl:1
	s_mov_b32 m0, s59
	ds_write_b32 v39, v15 offset:60640
	s_waitcnt vmcnt(29) lgkmcnt(6)
	v_cvt_pkrtz_f16_f32 v42, v32, v33
	v_dot2_f32_f16 v44, v60, v42, 0
	v_dot2_f32_f16 v45, v46, v42, 0
	v_cvt_pkrtz_f16_f32 v43, v34, v35
	v_pk_mul_f32 v[32:33], v[32:33], v[54:55]
	v_dot2c_f32_f16_e32 v44, v61, v43
	v_dot2c_f32_f16_e32 v45, v47, v43
	v_pk_mul_f32 v[34:35], v[34:35], v[56:57]
	ds_read_b128 v[12:15], v27 offset:17408
	v_add_f32_dpp v44, v44, v44 quad_perm:[1,0,3,2] row_mask:0xf bank_mask:0xf bound_ctrl:1
	ds_read_b128 v[18:21], v36 offset:17408
	ds_read_b128 v[22:25], v36 offset:17664
	v_add_f32_dpp v44, v44, v44 quad_perm:[2,3,0,1] row_mask:0xf bank_mask:0xf bound_ctrl:1
	ds_read_b32 v31, v37 offset:17408
	global_load_lds_dwordx4 v30, s[100:101]
	v_add_f32_dpp v44, v44, v44 row_half_mirror row_mask:0xf bank_mask:0xf bound_ctrl:1
	v_add_f32_dpp v45, v45, v45 quad_perm:[1,0,3,2] row_mask:0xf bank_mask:0xf bound_ctrl:1
	v_add_u32_e32 v30, s14, v30
	v_add_f32_dpp v44, v44, v44 row_mirror row_mask:0xf bank_mask:0xf bound_ctrl:1
	v_cvt_pkrtz_f16_f32 v44, v67, v44
	v_add_f32_dpp v45, v45, v45 quad_perm:[2,3,0,1] row_mask:0xf bank_mask:0xf bound_ctrl:1
	v_dot2c_f32_f16_e32 v32, v62, v44
	v_dot2c_f32_f16_e32 v33, v63, v44
	v_add_f32_dpp v45, v45, v45 row_half_mirror row_mask:0xf bank_mask:0xf bound_ctrl:1
	v_dot2c_f32_f16_e32 v34, v64, v44
	v_dot2c_f32_f16_e32 v35, v65, v44
	v_add_f32_dpp v45, v45, v45 row_mirror row_mask:0xf bank_mask:0xf bound_ctrl:1
	s_mov_b32 m0, s23
	ds_write_b32 v39, v45 offset:60656
	s_waitcnt vmcnt(29) lgkmcnt(6)
	v_cvt_pkrtz_f16_f32 v54, v32, v33
	v_dot2_f32_f16 v56, v6, v54, 0
	v_dot2_f32_f16 v57, v58, v54, 0
	v_cvt_pkrtz_f16_f32 v55, v34, v35
	v_pk_mul_f32 v[32:33], v[32:33], v[0:1]
	v_dot2c_f32_f16_e32 v56, v7, v55
	v_dot2c_f32_f16_e32 v57, v59, v55
	v_pk_mul_f32 v[34:35], v[34:35], v[2:3]
	ds_read_b128 v[42:45], v27 offset:18432
	v_add_f32_dpp v56, v56, v56 quad_perm:[1,0,3,2] row_mask:0xf bank_mask:0xf bound_ctrl:1
	ds_read_b128 v[46:49], v36 offset:18432
	ds_read_b128 v[50:53], v36 offset:18688
	v_add_f32_dpp v56, v56, v56 quad_perm:[2,3,0,1] row_mask:0xf bank_mask:0xf bound_ctrl:1
	ds_read_b32 v66, v37 offset:18432
	global_load_lds_dwordx4 v30, s[100:101]
	v_add_f32_dpp v56, v56, v56 row_half_mirror row_mask:0xf bank_mask:0xf bound_ctrl:1
	v_add_f32_dpp v57, v57, v57 quad_perm:[1,0,3,2] row_mask:0xf bank_mask:0xf bound_ctrl:1
	v_add_u32_e32 v30, s14, v30
	v_add_f32_dpp v56, v56, v56 row_mirror row_mask:0xf bank_mask:0xf bound_ctrl:1
	v_cvt_pkrtz_f16_f32 v56, v41, v56
	v_add_f32_dpp v57, v57, v57 quad_perm:[2,3,0,1] row_mask:0xf bank_mask:0xf bound_ctrl:1
	v_dot2c_f32_f16_e32 v32, v8, v56
	v_dot2c_f32_f16_e32 v33, v9, v56
	v_add_f32_dpp v57, v57, v57 row_half_mirror row_mask:0xf bank_mask:0xf bound_ctrl:1
	v_dot2c_f32_f16_e32 v34, v10, v56
	v_dot2c_f32_f16_e32 v35, v11, v56
	v_add_f32_dpp v57, v57, v57 row_mirror row_mask:0xf bank_mask:0xf bound_ctrl:1
	s_mov_b32 m0, s24
	ds_write_b32 v39, v57 offset:60672
	s_waitcnt vmcnt(29) lgkmcnt(6)
	v_cvt_pkrtz_f16_f32 v0, v32, v33
	v_dot2_f32_f16 v2, v20, v0, 0
	v_dot2_f32_f16 v3, v4, v0, 0
	v_cvt_pkrtz_f16_f32 v1, v34, v35
	v_pk_mul_f32 v[32:33], v[32:33], v[12:13]
	v_dot2c_f32_f16_e32 v2, v21, v1
	v_dot2c_f32_f16_e32 v3, v5, v1
	v_pk_mul_f32 v[34:35], v[34:35], v[14:15]
	ds_read_b128 v[54:57], v27 offset:19456
	v_add_f32_dpp v2, v2, v2 quad_perm:[1,0,3,2] row_mask:0xf bank_mask:0xf bound_ctrl:1
	ds_read_b128 v[58:61], v36 offset:19456
	ds_read_b128 v[62:65], v36 offset:19712
	v_add_f32_dpp v2, v2, v2 quad_perm:[2,3,0,1] row_mask:0xf bank_mask:0xf bound_ctrl:1
	ds_read_b32 v67, v37 offset:19456
	global_load_lds_dwordx4 v30, s[100:101]
	v_add_f32_dpp v2, v2, v2 row_half_mirror row_mask:0xf bank_mask:0xf bound_ctrl:1
	v_add_f32_dpp v3, v3, v3 quad_perm:[1,0,3,2] row_mask:0xf bank_mask:0xf bound_ctrl:1
	v_add_u32_e32 v30, s14, v30
	v_add_f32_dpp v2, v2, v2 row_mirror row_mask:0xf bank_mask:0xf bound_ctrl:1
	v_cvt_pkrtz_f16_f32 v2, v31, v2
	v_add_f32_dpp v3, v3, v3 quad_perm:[2,3,0,1] row_mask:0xf bank_mask:0xf bound_ctrl:1
	v_dot2c_f32_f16_e32 v32, v22, v2
	v_dot2c_f32_f16_e32 v33, v23, v2
	v_add_f32_dpp v3, v3, v3 row_half_mirror row_mask:0xf bank_mask:0xf bound_ctrl:1
	v_dot2c_f32_f16_e32 v34, v24, v2
	v_dot2c_f32_f16_e32 v35, v25, v2
	v_add_f32_dpp v3, v3, v3 row_mirror row_mask:0xf bank_mask:0xf bound_ctrl:1
	s_mov_b32 m0, s60
	ds_write_b32 v39, v3 offset:60688
	s_waitcnt vmcnt(29) lgkmcnt(6)
	v_cvt_pkrtz_f16_f32 v12, v32, v33
	v_dot2_f32_f16 v14, v48, v12, 0
	v_dot2_f32_f16 v15, v18, v12, 0
	v_cvt_pkrtz_f16_f32 v13, v34, v35
	v_pk_mul_f32 v[32:33], v[32:33], v[42:43]
	v_dot2c_f32_f16_e32 v14, v49, v13
	v_dot2c_f32_f16_e32 v15, v19, v13
	v_pk_mul_f32 v[34:35], v[34:35], v[44:45]
	ds_read_b128 v[0:3], v27 offset:20480
	v_add_f32_dpp v14, v14, v14 quad_perm:[1,0,3,2] row_mask:0xf bank_mask:0xf bound_ctrl:1
	ds_read_b128 v[4:7], v36 offset:20480
	ds_read_b128 v[8:11], v36 offset:20736
	v_add_f32_dpp v14, v14, v14 quad_perm:[2,3,0,1] row_mask:0xf bank_mask:0xf bound_ctrl:1
	ds_read_b32 v41, v37 offset:20480
	global_load_lds_dwordx4 v30, s[100:101]
	v_add_f32_dpp v14, v14, v14 row_half_mirror row_mask:0xf bank_mask:0xf bound_ctrl:1
	v_add_f32_dpp v15, v15, v15 quad_perm:[1,0,3,2] row_mask:0xf bank_mask:0xf bound_ctrl:1
	v_add_u32_e32 v30, s14, v30
	v_add_f32_dpp v14, v14, v14 row_mirror row_mask:0xf bank_mask:0xf bound_ctrl:1
	v_cvt_pkrtz_f16_f32 v14, v66, v14
	v_add_f32_dpp v15, v15, v15 quad_perm:[2,3,0,1] row_mask:0xf bank_mask:0xf bound_ctrl:1
	v_dot2c_f32_f16_e32 v32, v50, v14
	v_dot2c_f32_f16_e32 v33, v51, v14
	v_add_f32_dpp v15, v15, v15 row_half_mirror row_mask:0xf bank_mask:0xf bound_ctrl:1
	v_dot2c_f32_f16_e32 v34, v52, v14
	v_dot2c_f32_f16_e32 v35, v53, v14
	v_add_f32_dpp v15, v15, v15 row_mirror row_mask:0xf bank_mask:0xf bound_ctrl:1
	s_mov_b32 m0, s61
	ds_write_b32 v39, v15 offset:60704
	s_waitcnt vmcnt(29) lgkmcnt(6)
	v_cvt_pkrtz_f16_f32 v42, v32, v33
	v_dot2_f32_f16 v44, v60, v42, 0
	v_dot2_f32_f16 v45, v46, v42, 0
	v_cvt_pkrtz_f16_f32 v43, v34, v35
	v_pk_mul_f32 v[32:33], v[32:33], v[54:55]
	v_dot2c_f32_f16_e32 v44, v61, v43
	v_dot2c_f32_f16_e32 v45, v47, v43
	v_pk_mul_f32 v[34:35], v[34:35], v[56:57]
	ds_read_b128 v[12:15], v27 offset:21504
	v_add_f32_dpp v44, v44, v44 quad_perm:[1,0,3,2] row_mask:0xf bank_mask:0xf bound_ctrl:1
	ds_read_b128 v[18:21], v36 offset:21504
	ds_read_b128 v[22:25], v36 offset:21760
	v_add_f32_dpp v44, v44, v44 quad_perm:[2,3,0,1] row_mask:0xf bank_mask:0xf bound_ctrl:1
	ds_read_b32 v31, v37 offset:21504
	global_load_lds_dwordx4 v30, s[100:101]
	v_add_f32_dpp v44, v44, v44 row_half_mirror row_mask:0xf bank_mask:0xf bound_ctrl:1
	v_add_f32_dpp v45, v45, v45 quad_perm:[1,0,3,2] row_mask:0xf bank_mask:0xf bound_ctrl:1
	v_add_u32_e32 v30, s14, v30
	v_add_f32_dpp v44, v44, v44 row_mirror row_mask:0xf bank_mask:0xf bound_ctrl:1
	v_cvt_pkrtz_f16_f32 v44, v67, v44
	v_add_f32_dpp v45, v45, v45 quad_perm:[2,3,0,1] row_mask:0xf bank_mask:0xf bound_ctrl:1
	v_dot2c_f32_f16_e32 v32, v62, v44
	v_dot2c_f32_f16_e32 v33, v63, v44
	v_add_f32_dpp v45, v45, v45 row_half_mirror row_mask:0xf bank_mask:0xf bound_ctrl:1
	v_dot2c_f32_f16_e32 v34, v64, v44
	v_dot2c_f32_f16_e32 v35, v65, v44
	v_add_f32_dpp v45, v45, v45 row_mirror row_mask:0xf bank_mask:0xf bound_ctrl:1
	s_mov_b32 m0, s62
	ds_write_b32 v39, v45 offset:60720
	s_waitcnt vmcnt(29) lgkmcnt(6)
	v_cvt_pkrtz_f16_f32 v54, v32, v33
	v_dot2_f32_f16 v56, v6, v54, 0
	v_dot2_f32_f16 v57, v58, v54, 0
	v_cvt_pkrtz_f16_f32 v55, v34, v35
	v_pk_mul_f32 v[32:33], v[32:33], v[0:1]
	v_dot2c_f32_f16_e32 v56, v7, v55
	v_dot2c_f32_f16_e32 v57, v59, v55
	v_pk_mul_f32 v[34:35], v[34:35], v[2:3]
	ds_read_b128 v[42:45], v27 offset:22528
	v_add_f32_dpp v56, v56, v56 quad_perm:[1,0,3,2] row_mask:0xf bank_mask:0xf bound_ctrl:1
	ds_read_b128 v[46:49], v36 offset:22528
	ds_read_b128 v[50:53], v36 offset:22784
	v_add_f32_dpp v56, v56, v56 quad_perm:[2,3,0,1] row_mask:0xf bank_mask:0xf bound_ctrl:1
	ds_read_b32 v66, v37 offset:22528
	global_load_lds_dwordx4 v30, s[100:101]
	v_add_f32_dpp v56, v56, v56 row_half_mirror row_mask:0xf bank_mask:0xf bound_ctrl:1
	v_add_f32_dpp v57, v57, v57 quad_perm:[1,0,3,2] row_mask:0xf bank_mask:0xf bound_ctrl:1
	v_add_u32_e32 v30, s14, v30
	v_add_f32_dpp v56, v56, v56 row_mirror row_mask:0xf bank_mask:0xf bound_ctrl:1
	v_cvt_pkrtz_f16_f32 v56, v41, v56
	v_add_f32_dpp v57, v57, v57 quad_perm:[2,3,0,1] row_mask:0xf bank_mask:0xf bound_ctrl:1
	v_dot2c_f32_f16_e32 v32, v8, v56
	v_dot2c_f32_f16_e32 v33, v9, v56
	v_add_f32_dpp v57, v57, v57 row_half_mirror row_mask:0xf bank_mask:0xf bound_ctrl:1
	v_dot2c_f32_f16_e32 v34, v10, v56
	v_dot2c_f32_f16_e32 v35, v11, v56
	v_add_f32_dpp v57, v57, v57 row_mirror row_mask:0xf bank_mask:0xf bound_ctrl:1
	s_mov_b32 m0, s63
	ds_write_b32 v39, v57 offset:60736
	s_waitcnt vmcnt(29) lgkmcnt(6)
	v_cvt_pkrtz_f16_f32 v0, v32, v33
	v_dot2_f32_f16 v2, v20, v0, 0
	v_dot2_f32_f16 v3, v4, v0, 0
	v_cvt_pkrtz_f16_f32 v1, v34, v35
	v_pk_mul_f32 v[32:33], v[32:33], v[12:13]
	v_dot2c_f32_f16_e32 v2, v21, v1
	v_dot2c_f32_f16_e32 v3, v5, v1
	v_pk_mul_f32 v[34:35], v[34:35], v[14:15]
	ds_read_b128 v[54:57], v27 offset:23552
	v_add_f32_dpp v2, v2, v2 quad_perm:[1,0,3,2] row_mask:0xf bank_mask:0xf bound_ctrl:1
	ds_read_b128 v[58:61], v36 offset:23552
	ds_read_b128 v[62:65], v36 offset:23808
	v_add_f32_dpp v2, v2, v2 quad_perm:[2,3,0,1] row_mask:0xf bank_mask:0xf bound_ctrl:1
	ds_read_b32 v67, v37 offset:23552
	global_load_lds_dwordx4 v30, s[100:101]
	v_add_f32_dpp v2, v2, v2 row_half_mirror row_mask:0xf bank_mask:0xf bound_ctrl:1
	v_add_f32_dpp v3, v3, v3 quad_perm:[1,0,3,2] row_mask:0xf bank_mask:0xf bound_ctrl:1
	v_add_u32_e32 v30, s14, v30
	v_add_f32_dpp v2, v2, v2 row_mirror row_mask:0xf bank_mask:0xf bound_ctrl:1
	v_cvt_pkrtz_f16_f32 v2, v31, v2
	v_add_f32_dpp v3, v3, v3 quad_perm:[2,3,0,1] row_mask:0xf bank_mask:0xf bound_ctrl:1
	v_dot2c_f32_f16_e32 v32, v22, v2
	v_dot2c_f32_f16_e32 v33, v23, v2
	v_add_f32_dpp v3, v3, v3 row_half_mirror row_mask:0xf bank_mask:0xf bound_ctrl:1
	v_dot2c_f32_f16_e32 v34, v24, v2
	v_dot2c_f32_f16_e32 v35, v25, v2
	v_add_f32_dpp v3, v3, v3 row_mirror row_mask:0xf bank_mask:0xf bound_ctrl:1
	s_mov_b32 m0, s64
	ds_write_b32 v39, v3 offset:60752
	s_waitcnt vmcnt(29) lgkmcnt(6)
	v_cvt_pkrtz_f16_f32 v12, v32, v33
	v_dot2_f32_f16 v14, v48, v12, 0
	v_dot2_f32_f16 v15, v18, v12, 0
	v_cvt_pkrtz_f16_f32 v13, v34, v35
	v_pk_mul_f32 v[32:33], v[32:33], v[42:43]
	v_dot2c_f32_f16_e32 v14, v49, v13
	v_dot2c_f32_f16_e32 v15, v19, v13
	v_pk_mul_f32 v[34:35], v[34:35], v[44:45]
	ds_read_b128 v[0:3], v27 offset:24576
	v_add_f32_dpp v14, v14, v14 quad_perm:[1,0,3,2] row_mask:0xf bank_mask:0xf bound_ctrl:1
	ds_read_b128 v[4:7], v36 offset:24576
	ds_read_b128 v[8:11], v36 offset:24832
	v_add_f32_dpp v14, v14, v14 quad_perm:[2,3,0,1] row_mask:0xf bank_mask:0xf bound_ctrl:1
	ds_read_b32 v41, v37 offset:24576
	global_load_lds_dwordx4 v30, s[100:101]
	v_add_f32_dpp v14, v14, v14 row_half_mirror row_mask:0xf bank_mask:0xf bound_ctrl:1
	v_add_f32_dpp v15, v15, v15 quad_perm:[1,0,3,2] row_mask:0xf bank_mask:0xf bound_ctrl:1
	v_add_u32_e32 v30, s14, v30
	v_add_f32_dpp v14, v14, v14 row_mirror row_mask:0xf bank_mask:0xf bound_ctrl:1
	v_cvt_pkrtz_f16_f32 v14, v66, v14
	v_add_f32_dpp v15, v15, v15 quad_perm:[2,3,0,1] row_mask:0xf bank_mask:0xf bound_ctrl:1
	v_dot2c_f32_f16_e32 v32, v50, v14
	v_dot2c_f32_f16_e32 v33, v51, v14
	v_add_f32_dpp v15, v15, v15 row_half_mirror row_mask:0xf bank_mask:0xf bound_ctrl:1
	v_dot2c_f32_f16_e32 v34, v52, v14
	v_dot2c_f32_f16_e32 v35, v53, v14
	v_add_f32_dpp v15, v15, v15 row_mirror row_mask:0xf bank_mask:0xf bound_ctrl:1
	s_mov_b32 m0, s65
	ds_write_b32 v39, v15 offset:60768
	s_waitcnt vmcnt(29) lgkmcnt(6)
	v_cvt_pkrtz_f16_f32 v42, v32, v33
	v_dot2_f32_f16 v44, v60, v42, 0
	v_dot2_f32_f16 v45, v46, v42, 0
	v_cvt_pkrtz_f16_f32 v43, v34, v35
	v_pk_mul_f32 v[32:33], v[32:33], v[54:55]
	v_dot2c_f32_f16_e32 v44, v61, v43
	v_dot2c_f32_f16_e32 v45, v47, v43
	v_pk_mul_f32 v[34:35], v[34:35], v[56:57]
	ds_read_b128 v[12:15], v27 offset:25600
	v_add_f32_dpp v44, v44, v44 quad_perm:[1,0,3,2] row_mask:0xf bank_mask:0xf bound_ctrl:1
	ds_read_b128 v[18:21], v36 offset:25600
	ds_read_b128 v[22:25], v36 offset:25856
	v_add_f32_dpp v44, v44, v44 quad_perm:[2,3,0,1] row_mask:0xf bank_mask:0xf bound_ctrl:1
	ds_read_b32 v31, v37 offset:25600
	global_load_lds_dwordx4 v30, s[100:101]
	v_add_f32_dpp v44, v44, v44 row_half_mirror row_mask:0xf bank_mask:0xf bound_ctrl:1
	v_add_f32_dpp v45, v45, v45 quad_perm:[1,0,3,2] row_mask:0xf bank_mask:0xf bound_ctrl:1
	v_add_u32_e32 v30, s14, v30
	v_add_f32_dpp v44, v44, v44 row_mirror row_mask:0xf bank_mask:0xf bound_ctrl:1
	v_cvt_pkrtz_f16_f32 v44, v67, v44
	v_add_f32_dpp v45, v45, v45 quad_perm:[2,3,0,1] row_mask:0xf bank_mask:0xf bound_ctrl:1
	v_dot2c_f32_f16_e32 v32, v62, v44
	v_dot2c_f32_f16_e32 v33, v63, v44
	v_add_f32_dpp v45, v45, v45 row_half_mirror row_mask:0xf bank_mask:0xf bound_ctrl:1
	v_dot2c_f32_f16_e32 v34, v64, v44
	v_dot2c_f32_f16_e32 v35, v65, v44
	v_add_f32_dpp v45, v45, v45 row_mirror row_mask:0xf bank_mask:0xf bound_ctrl:1
	s_mov_b32 m0, s66
	ds_write_b32 v39, v45 offset:60784
	s_waitcnt vmcnt(29) lgkmcnt(6)
	v_cvt_pkrtz_f16_f32 v54, v32, v33
	v_dot2_f32_f16 v56, v6, v54, 0
	v_dot2_f32_f16 v57, v58, v54, 0
	v_cvt_pkrtz_f16_f32 v55, v34, v35
	v_pk_mul_f32 v[32:33], v[32:33], v[0:1]
	v_dot2c_f32_f16_e32 v56, v7, v55
	v_dot2c_f32_f16_e32 v57, v59, v55
	v_pk_mul_f32 v[34:35], v[34:35], v[2:3]
	ds_read_b128 v[42:45], v27 offset:26624
	v_add_f32_dpp v56, v56, v56 quad_perm:[1,0,3,2] row_mask:0xf bank_mask:0xf bound_ctrl:1
	ds_read_b128 v[46:49], v36 offset:26624
	ds_read_b128 v[50:53], v36 offset:26880
	v_add_f32_dpp v56, v56, v56 quad_perm:[2,3,0,1] row_mask:0xf bank_mask:0xf bound_ctrl:1
	ds_read_b32 v66, v37 offset:26624
	global_load_lds_dwordx4 v30, s[100:101]
	v_add_f32_dpp v56, v56, v56 row_half_mirror row_mask:0xf bank_mask:0xf bound_ctrl:1
	v_add_f32_dpp v57, v57, v57 quad_perm:[1,0,3,2] row_mask:0xf bank_mask:0xf bound_ctrl:1
	v_add_u32_e32 v30, s14, v30
	v_add_f32_dpp v56, v56, v56 row_mirror row_mask:0xf bank_mask:0xf bound_ctrl:1
	v_cvt_pkrtz_f16_f32 v56, v41, v56
	v_add_f32_dpp v57, v57, v57 quad_perm:[2,3,0,1] row_mask:0xf bank_mask:0xf bound_ctrl:1
	v_dot2c_f32_f16_e32 v32, v8, v56
	v_dot2c_f32_f16_e32 v33, v9, v56
	v_add_f32_dpp v57, v57, v57 row_half_mirror row_mask:0xf bank_mask:0xf bound_ctrl:1
	v_dot2c_f32_f16_e32 v34, v10, v56
	v_dot2c_f32_f16_e32 v35, v11, v56
	v_add_f32_dpp v57, v57, v57 row_mirror row_mask:0xf bank_mask:0xf bound_ctrl:1
	s_mov_b32 m0, s67
	ds_write_b32 v39, v57 offset:60800
	s_waitcnt vmcnt(29) lgkmcnt(6)
	v_cvt_pkrtz_f16_f32 v0, v32, v33
	v_dot2_f32_f16 v2, v20, v0, 0
	v_dot2_f32_f16 v3, v4, v0, 0
	v_cvt_pkrtz_f16_f32 v1, v34, v35
	v_pk_mul_f32 v[32:33], v[32:33], v[12:13]
	v_dot2c_f32_f16_e32 v2, v21, v1
	v_dot2c_f32_f16_e32 v3, v5, v1
	v_pk_mul_f32 v[34:35], v[34:35], v[14:15]
	ds_read_b128 v[54:57], v27 offset:27648
	v_add_f32_dpp v2, v2, v2 quad_perm:[1,0,3,2] row_mask:0xf bank_mask:0xf bound_ctrl:1
	ds_read_b128 v[58:61], v36 offset:27648
	ds_read_b128 v[62:65], v36 offset:27904
	v_add_f32_dpp v2, v2, v2 quad_perm:[2,3,0,1] row_mask:0xf bank_mask:0xf bound_ctrl:1
	ds_read_b32 v67, v37 offset:27648
	global_load_lds_dwordx4 v30, s[100:101]
	v_add_f32_dpp v2, v2, v2 row_half_mirror row_mask:0xf bank_mask:0xf bound_ctrl:1
	v_add_f32_dpp v3, v3, v3 quad_perm:[1,0,3,2] row_mask:0xf bank_mask:0xf bound_ctrl:1
	v_add_u32_e32 v30, s14, v30
	v_add_f32_dpp v2, v2, v2 row_mirror row_mask:0xf bank_mask:0xf bound_ctrl:1
	v_cvt_pkrtz_f16_f32 v2, v31, v2
	v_add_f32_dpp v3, v3, v3 quad_perm:[2,3,0,1] row_mask:0xf bank_mask:0xf bound_ctrl:1
	v_dot2c_f32_f16_e32 v32, v22, v2
	v_dot2c_f32_f16_e32 v33, v23, v2
	v_add_f32_dpp v3, v3, v3 row_half_mirror row_mask:0xf bank_mask:0xf bound_ctrl:1
	v_dot2c_f32_f16_e32 v34, v24, v2
	v_dot2c_f32_f16_e32 v35, v25, v2
	v_add_f32_dpp v3, v3, v3 row_mirror row_mask:0xf bank_mask:0xf bound_ctrl:1
	s_mov_b32 m0, s69
	ds_write_b32 v39, v3 offset:60816
	s_waitcnt vmcnt(29) lgkmcnt(6)
	v_cvt_pkrtz_f16_f32 v12, v32, v33
	v_dot2_f32_f16 v14, v48, v12, 0
	v_dot2_f32_f16 v15, v18, v12, 0
	v_cvt_pkrtz_f16_f32 v13, v34, v35
	v_pk_mul_f32 v[32:33], v[32:33], v[42:43]
	v_dot2c_f32_f16_e32 v14, v49, v13
	v_dot2c_f32_f16_e32 v15, v19, v13
	v_pk_mul_f32 v[34:35], v[34:35], v[44:45]
	ds_read_b128 v[0:3], v27 offset:28672
	v_add_f32_dpp v14, v14, v14 quad_perm:[1,0,3,2] row_mask:0xf bank_mask:0xf bound_ctrl:1
	ds_read_b128 v[4:7], v36 offset:28672
	ds_read_b128 v[8:11], v36 offset:28928
	v_add_f32_dpp v14, v14, v14 quad_perm:[2,3,0,1] row_mask:0xf bank_mask:0xf bound_ctrl:1
	ds_read_b32 v41, v37 offset:28672
	global_load_lds_dwordx4 v30, s[100:101]
	v_add_f32_dpp v14, v14, v14 row_half_mirror row_mask:0xf bank_mask:0xf bound_ctrl:1
	v_add_f32_dpp v15, v15, v15 quad_perm:[1,0,3,2] row_mask:0xf bank_mask:0xf bound_ctrl:1
	v_add_u32_e32 v30, s14, v30
	v_add_f32_dpp v14, v14, v14 row_mirror row_mask:0xf bank_mask:0xf bound_ctrl:1
	v_cvt_pkrtz_f16_f32 v14, v66, v14
	v_add_f32_dpp v15, v15, v15 quad_perm:[2,3,0,1] row_mask:0xf bank_mask:0xf bound_ctrl:1
	v_dot2c_f32_f16_e32 v32, v50, v14
	v_dot2c_f32_f16_e32 v33, v51, v14
	v_add_f32_dpp v15, v15, v15 row_half_mirror row_mask:0xf bank_mask:0xf bound_ctrl:1
	v_dot2c_f32_f16_e32 v34, v52, v14
	v_dot2c_f32_f16_e32 v35, v53, v14
	v_add_f32_dpp v15, v15, v15 row_mirror row_mask:0xf bank_mask:0xf bound_ctrl:1
	s_mov_b32 m0, s70
	ds_write_b32 v39, v15 offset:60832
	s_waitcnt vmcnt(29) lgkmcnt(6)
	v_cvt_pkrtz_f16_f32 v42, v32, v33
	v_dot2_f32_f16 v44, v60, v42, 0
	v_dot2_f32_f16 v45, v46, v42, 0
	v_cvt_pkrtz_f16_f32 v43, v34, v35
	v_pk_mul_f32 v[32:33], v[32:33], v[54:55]
	v_dot2c_f32_f16_e32 v44, v61, v43
	v_dot2c_f32_f16_e32 v45, v47, v43
	v_pk_mul_f32 v[34:35], v[34:35], v[56:57]
	ds_read_b128 v[12:15], v27 offset:29696
	v_add_f32_dpp v44, v44, v44 quad_perm:[1,0,3,2] row_mask:0xf bank_mask:0xf bound_ctrl:1
	ds_read_b128 v[18:21], v36 offset:29696
	ds_read_b128 v[22:25], v36 offset:29952
	v_add_f32_dpp v44, v44, v44 quad_perm:[2,3,0,1] row_mask:0xf bank_mask:0xf bound_ctrl:1
	ds_read_b32 v31, v37 offset:29696
	global_load_lds_dwordx4 v30, s[100:101]
	v_add_f32_dpp v44, v44, v44 row_half_mirror row_mask:0xf bank_mask:0xf bound_ctrl:1
	v_add_f32_dpp v45, v45, v45 quad_perm:[1,0,3,2] row_mask:0xf bank_mask:0xf bound_ctrl:1
	v_add_u32_e32 v30, s14, v30
	v_add_f32_dpp v44, v44, v44 row_mirror row_mask:0xf bank_mask:0xf bound_ctrl:1
	v_cvt_pkrtz_f16_f32 v44, v67, v44
	v_add_f32_dpp v45, v45, v45 quad_perm:[2,3,0,1] row_mask:0xf bank_mask:0xf bound_ctrl:1
	v_dot2c_f32_f16_e32 v32, v62, v44
	v_dot2c_f32_f16_e32 v33, v63, v44
	v_add_f32_dpp v45, v45, v45 row_half_mirror row_mask:0xf bank_mask:0xf bound_ctrl:1
	v_dot2c_f32_f16_e32 v34, v64, v44
	v_dot2c_f32_f16_e32 v35, v65, v44
	v_add_f32_dpp v45, v45, v45 row_mirror row_mask:0xf bank_mask:0xf bound_ctrl:1
	s_mov_b32 m0, s71
	ds_write_b32 v39, v45 offset:60848
	s_waitcnt vmcnt(29) lgkmcnt(6)
	v_cvt_pkrtz_f16_f32 v54, v32, v33
	v_dot2_f32_f16 v56, v6, v54, 0
	v_dot2_f32_f16 v57, v58, v54, 0
	v_cvt_pkrtz_f16_f32 v55, v34, v35
	v_pk_mul_f32 v[32:33], v[32:33], v[0:1]
	v_dot2c_f32_f16_e32 v56, v7, v55
	v_dot2c_f32_f16_e32 v57, v59, v55
	v_pk_mul_f32 v[34:35], v[34:35], v[2:3]
	ds_read_b128 v[42:45], v27 offset:30720
	v_add_f32_dpp v56, v56, v56 quad_perm:[1,0,3,2] row_mask:0xf bank_mask:0xf bound_ctrl:1
	ds_read_b128 v[46:49], v36 offset:30720
	ds_read_b128 v[50:53], v36 offset:30976
	v_add_f32_dpp v56, v56, v56 quad_perm:[2,3,0,1] row_mask:0xf bank_mask:0xf bound_ctrl:1
	ds_read_b32 v66, v37 offset:30720
	global_load_lds_dwordx4 v30, s[100:101]
	v_add_f32_dpp v56, v56, v56 row_half_mirror row_mask:0xf bank_mask:0xf bound_ctrl:1
	v_add_f32_dpp v57, v57, v57 quad_perm:[1,0,3,2] row_mask:0xf bank_mask:0xf bound_ctrl:1
	v_add_u32_e32 v30, s14, v30
	v_add_f32_dpp v56, v56, v56 row_mirror row_mask:0xf bank_mask:0xf bound_ctrl:1
	v_cvt_pkrtz_f16_f32 v56, v41, v56
	v_add_f32_dpp v57, v57, v57 quad_perm:[2,3,0,1] row_mask:0xf bank_mask:0xf bound_ctrl:1
	v_dot2c_f32_f16_e32 v32, v8, v56
	v_dot2c_f32_f16_e32 v33, v9, v56
	v_add_f32_dpp v57, v57, v57 row_half_mirror row_mask:0xf bank_mask:0xf bound_ctrl:1
	v_dot2c_f32_f16_e32 v34, v10, v56
	v_dot2c_f32_f16_e32 v35, v11, v56
	v_add_f32_dpp v57, v57, v57 row_mirror row_mask:0xf bank_mask:0xf bound_ctrl:1
	s_mov_b32 m0, s26
	ds_write_b32 v39, v57 offset:60864
	s_waitcnt vmcnt(29) lgkmcnt(6)
	v_cvt_pkrtz_f16_f32 v0, v32, v33
	v_dot2_f32_f16 v2, v20, v0, 0
	v_dot2_f32_f16 v3, v4, v0, 0
	v_cvt_pkrtz_f16_f32 v1, v34, v35
	v_pk_mul_f32 v[32:33], v[32:33], v[12:13]
	v_dot2c_f32_f16_e32 v2, v21, v1
	v_dot2c_f32_f16_e32 v3, v5, v1
	v_pk_mul_f32 v[34:35], v[34:35], v[14:15]
	ds_read_b128 v[54:57], v27 offset:31744
	v_add_f32_dpp v2, v2, v2 quad_perm:[1,0,3,2] row_mask:0xf bank_mask:0xf bound_ctrl:1
	ds_read_b128 v[58:61], v36 offset:31744
	ds_read_b128 v[62:65], v36 offset:32000
	v_add_f32_dpp v2, v2, v2 quad_perm:[2,3,0,1] row_mask:0xf bank_mask:0xf bound_ctrl:1
	ds_read_b32 v67, v37 offset:31744
	global_load_lds_dwordx4 v30, s[100:101]
	v_add_f32_dpp v2, v2, v2 row_half_mirror row_mask:0xf bank_mask:0xf bound_ctrl:1
	v_add_f32_dpp v3, v3, v3 quad_perm:[1,0,3,2] row_mask:0xf bank_mask:0xf bound_ctrl:1
	v_add_u32_e32 v30, s14, v30
	v_add_f32_dpp v2, v2, v2 row_mirror row_mask:0xf bank_mask:0xf bound_ctrl:1
	v_cvt_pkrtz_f16_f32 v2, v31, v2
	v_add_f32_dpp v3, v3, v3 quad_perm:[2,3,0,1] row_mask:0xf bank_mask:0xf bound_ctrl:1
	v_dot2c_f32_f16_e32 v32, v22, v2
	v_dot2c_f32_f16_e32 v33, v23, v2
	v_add_f32_dpp v3, v3, v3 row_half_mirror row_mask:0xf bank_mask:0xf bound_ctrl:1
	v_dot2c_f32_f16_e32 v34, v24, v2
	v_dot2c_f32_f16_e32 v35, v25, v2
	v_add_f32_dpp v3, v3, v3 row_mirror row_mask:0xf bank_mask:0xf bound_ctrl:1
	s_mov_b32 m0, s72
	ds_write_b32 v39, v3 offset:60880
	s_waitcnt vmcnt(29) lgkmcnt(6)
	v_cvt_pkrtz_f16_f32 v12, v32, v33
	v_dot2_f32_f16 v14, v48, v12, 0
	v_dot2_f32_f16 v15, v18, v12, 0
	v_cvt_pkrtz_f16_f32 v13, v34, v35
	v_pk_mul_f32 v[32:33], v[32:33], v[42:43]
	v_dot2c_f32_f16_e32 v14, v49, v13
	v_dot2c_f32_f16_e32 v15, v19, v13
	v_pk_mul_f32 v[34:35], v[34:35], v[44:45]
	ds_read_b128 v[0:3], v27 offset:0
	v_add_f32_dpp v14, v14, v14 quad_perm:[1,0,3,2] row_mask:0xf bank_mask:0xf bound_ctrl:1
	ds_read_b128 v[4:7], v36 offset:0
	ds_read_b128 v[8:11], v36 offset:256
	v_add_f32_dpp v14, v14, v14 quad_perm:[2,3,0,1] row_mask:0xf bank_mask:0xf bound_ctrl:1
	ds_read_b32 v41, v37 offset:0
	global_load_lds_dwordx4 v30, s[100:101]
	v_add_f32_dpp v14, v14, v14 row_half_mirror row_mask:0xf bank_mask:0xf bound_ctrl:1
	v_add_f32_dpp v15, v15, v15 quad_perm:[1,0,3,2] row_mask:0xf bank_mask:0xf bound_ctrl:1
	v_add_u32_e32 v30, s14, v30
	v_add_f32_dpp v14, v14, v14 row_mirror row_mask:0xf bank_mask:0xf bound_ctrl:1
	v_cvt_pkrtz_f16_f32 v14, v66, v14
	v_add_f32_dpp v15, v15, v15 quad_perm:[2,3,0,1] row_mask:0xf bank_mask:0xf bound_ctrl:1
	v_dot2c_f32_f16_e32 v32, v50, v14
	v_dot2c_f32_f16_e32 v33, v51, v14
	v_add_f32_dpp v15, v15, v15 row_half_mirror row_mask:0xf bank_mask:0xf bound_ctrl:1
	v_dot2c_f32_f16_e32 v34, v52, v14
	v_dot2c_f32_f16_e32 v35, v53, v14
	v_add_f32_dpp v15, v15, v15 row_mirror row_mask:0xf bank_mask:0xf bound_ctrl:1
	s_mov_b32 m0, s73
	ds_write_b32 v39, v15 offset:60896
	s_waitcnt vmcnt(29) lgkmcnt(6)
	v_cvt_pkrtz_f16_f32 v42, v32, v33
	v_dot2_f32_f16 v44, v60, v42, 0
	v_dot2_f32_f16 v45, v46, v42, 0
	v_cvt_pkrtz_f16_f32 v43, v34, v35
	v_pk_mul_f32 v[32:33], v[32:33], v[54:55]
	v_dot2c_f32_f16_e32 v44, v61, v43
	v_dot2c_f32_f16_e32 v45, v47, v43
	v_pk_mul_f32 v[34:35], v[34:35], v[56:57]
	ds_read_b128 v[12:15], v27 offset:1024
	v_add_f32_dpp v44, v44, v44 quad_perm:[1,0,3,2] row_mask:0xf bank_mask:0xf bound_ctrl:1
	ds_read_b128 v[18:21], v36 offset:1024
	ds_read_b128 v[22:25], v36 offset:1280
	v_add_f32_dpp v44, v44, v44 quad_perm:[2,3,0,1] row_mask:0xf bank_mask:0xf bound_ctrl:1
	ds_read_b32 v31, v37 offset:1024
	global_load_lds_dwordx4 v30, s[100:101]
	v_add_f32_dpp v44, v44, v44 row_half_mirror row_mask:0xf bank_mask:0xf bound_ctrl:1
	v_add_f32_dpp v45, v45, v45 quad_perm:[1,0,3,2] row_mask:0xf bank_mask:0xf bound_ctrl:1
	v_add_u32_e32 v30, s14, v30
	v_add_f32_dpp v44, v44, v44 row_mirror row_mask:0xf bank_mask:0xf bound_ctrl:1
	v_cvt_pkrtz_f16_f32 v44, v67, v44
	v_add_f32_dpp v45, v45, v45 quad_perm:[2,3,0,1] row_mask:0xf bank_mask:0xf bound_ctrl:1
	v_dot2c_f32_f16_e32 v32, v62, v44
	v_dot2c_f32_f16_e32 v33, v63, v44
	v_add_f32_dpp v45, v45, v45 row_half_mirror row_mask:0xf bank_mask:0xf bound_ctrl:1
	v_dot2c_f32_f16_e32 v34, v64, v44
	v_dot2c_f32_f16_e32 v35, v65, v44
	v_add_f32_dpp v45, v45, v45 row_mirror row_mask:0xf bank_mask:0xf bound_ctrl:1
	s_mov_b32 m0, s43
	ds_write_b32 v39, v45 offset:60912
	ds_read_b64 v[50:51], v40 offset:60416
	s_waitcnt vmcnt(29) lgkmcnt(7)
	s_waitcnt lgkmcnt(0)
	v_cmp_ne_u32_e32 vcc, s27, v38
	s_and_saveexec_b64 s[4:5], vcc
	v_cvt_f16_f32_sdwa v52, v51 dst_sel:WORD_1 dst_unused:UNUSED_PAD src0_sel:DWORD
	v_cvt_f16_f32_e32 v53, v50
	v_or_b32_e32 v52, v52, v53
	global_store_dword v[28:29], v52, off
	s_or_b64 exec, exec, s[4:5]
	s_mov_b64 s[4:5], 0x20000
	v_lshl_add_u64 v[28:29], v[28:29], 0, s[4:5]
	s_cmpk_lt_u32 s27, 0x3fe0
	s_cbranch_scc0 .Lscan_exit
	s_add_i32 s27, s27, 32
	s_branch .Lscan_loop
.Lscan_exit:
	s_waitcnt lgkmcnt(0)
	v_mov_b32_e32 v12, v58
	v_mov_b32_e32 v13, v59
	s_branch .LBB0_694
